# h_fold row pass: non-temporal hint on the f32 x row loads (plus the out-projection residual nt loads)
# speedup vs baseline: 1.0202x; 1.0186x over previous
; __device__ __forceinline__ void pass_h_fold(const float* src, const float* g, const float* mod, bf16_t* H, bf16_t* HE, bf16_t* HO) {
;     const int vb = (gridDim.x & 7) ? (int)blockIdx.x : (int)((blockIdx.x & 7) * (gridDim.x >> 3) + (blockIdx.x >> 3));
;     const int lane = threadIdx.x & 63, gw = vb * NWAVES + (threadIdx.x >> 6), NGW = gridDim.x * NWAVES;
;     for (int ch = gw; ch < 2048; ch += NGW) {
;         const int b = ch >> 8, sb = (ch & 255) * 4;
;         f32x4 mul[4], sh[4];
; #pragma unroll
;         for (int j = 0; j < 4; ++j) { const f32x4 gg = ((const f32x4*)g)[lane + 64 * j], sc = ((const f32x4*)(mod + (size_t)b * NMOD + DM))[lane + 64 * j];
;             mul[j] = gg * (1.0f + sc); sh[j] = ((const f32x4*)(mod + (size_t)b * NMOD))[lane + 64 * j]; }
; #pragma unroll
;         for (int half = 0; half < 2; ++half) {
;             f32x4 v[2][2][4];
; #pragma unroll
;             for (int q = 0; q < 2; ++q) { const int s = sb + half * 2 + q, pr = (s == 0) ? SEQ / 2 : SEQ - s;
;                 const f32x4* x0 = (const f32x4*)(src + (size_t)(b * SEQ + s) * DM) + lane; const f32x4* x1 = (const f32x4*)(src + (size_t)(b * SEQ + pr) * DM) + lane;
; #pragma unroll
;                 for (int j = 0; j < 4; ++j) { v[q][0][j] = x0[64 * j]; v[q][1][j] = x1[64 * j]; } }
.LBB0_99:
	v_ashrrev_i32_e32 v16, 8, v173
	v_and_b32_e32 v17, 0x3fc, v180
	v_mul_hi_i32_i24_e32 v19, 0x6000, v16
	v_mul_i32_i24_e32 v18, 0x6000, v16
	v_lshlrev_b32_e32 v20, 11, v16
	v_lshlrev_b32_e32 v16, 10, v16
	v_or_b32_e32 v22, 1, v17
	v_or_b32_e32 v23, 2, v17
	v_or_b32_e32 v37, 3, v17
	v_lshl_add_u64 v[18:19], s[34:35], 0, v[18:19]
	v_or_b32_e32 v24, v17, v20
	v_sub_u32_e32 v21, 0x800, v17
	v_cmp_eq_u32_e64 s[4:5], 0, v17
	v_or_b32_e32 v26, v22, v20
	v_or_b32_e32 v28, v17, v16
	v_or_b32_e32 v30, v22, v16
	v_or_b32_e32 v32, v23, v20
	v_or_b32_e32 v34, v37, v20
	v_lshl_add_u64 v[40:41], v[18:19], 0, s[24:25]
	v_ashrrev_i32_e32 v25, 31, v24
	v_cndmask_b32_e64 v21, v21, v181, s[4:5]
	v_add_u32_e32 v39, 0x800, v20
	v_lshl_add_u64 v[42:43], v[18:19], 0, v[96:97]
	v_ashrrev_i32_e32 v27, 31, v26
	v_ashrrev_i32_e32 v29, 31, v28
	v_ashrrev_i32_e32 v31, 31, v30
	v_ashrrev_i32_e32 v33, 31, v32
	v_ashrrev_i32_e32 v35, 31, v34
	v_lshl_add_u64 v[52:53], v[40:41], 0, v[96:97]
	v_lshl_add_u64 v[54:55], v[40:41], 0, v[108:109]
	v_lshl_add_u64 v[56:57], v[40:41], 0, v[110:111]
	v_lshl_add_u64 v[40:41], v[40:41], 0, v[112:113]
	v_lshlrev_b64 v[58:59], 12, v[24:25]
	global_load_dwordx4 v[0:3], v[106:107], off
	global_load_dwordx4 v[4:7], v[106:107], off offset:1024
	global_load_dwordx4 v[8:11], v[106:107], off offset:2048
	global_load_dwordx4 v[12:15], v[106:107], off offset:3072
	v_or_b32_e32 v36, v23, v16
	v_or_b32_e32 v38, v37, v16
	v_add_u32_e32 v44, v21, v20
	v_sub_u32_e32 v46, v39, v22
	v_sub_u32_e32 v48, v39, v23
	v_sub_u32_e32 v50, v39, v37
	global_load_dwordx4 v[20:23], v[42:43], off offset:1024
	global_load_dwordx4 v[16:19], v[42:43], off offset:2048
	v_lshlrev_b64 v[60:61], 12, v[26:27]
	v_lshlrev_b64 v[62:63], 11, v[24:25]
	v_lshlrev_b64 v[64:65], 11, v[28:29]
	v_lshlrev_b64 v[66:67], 11, v[26:27]
	v_lshlrev_b64 v[68:69], 11, v[30:31]
	v_lshlrev_b64 v[70:71], 12, v[32:33]
	v_lshlrev_b64 v[72:73], 12, v[34:35]
	global_load_dwordx4 v[130:133], v[52:53], off
	global_load_dwordx4 v[28:31], v[42:43], off
	global_load_dwordx4 v[134:137], v[56:57], off
	global_load_dwordx4 v[138:141], v[40:41], off
	global_load_dwordx4 v[142:145], v[54:55], off
	global_load_dwordx4 v[24:27], v[42:43], off offset:3072
	v_lshl_add_u64 v[40:41], v[98:99], 0, v[58:59]
	v_ashrrev_i32_e32 v37, 31, v36
	v_ashrrev_i32_e32 v39, 31, v38
	v_ashrrev_i32_e32 v45, 31, v44
	v_ashrrev_i32_e32 v47, 31, v46
	v_ashrrev_i32_e32 v49, 31, v48
	v_ashrrev_i32_e32 v51, 31, v50
	v_lshlrev_b64 v[32:33], 11, v[32:33]
	v_lshlrev_b64 v[34:35], 11, v[34:35]
	v_lshl_add_u64 v[80:81], v[98:99], 0, v[60:61]
	v_lshl_add_u64 v[152:153], v[102:103], 0, v[68:69]
	v_lshl_add_u64 v[150:151], v[104:105], 0, v[68:69]
	v_lshl_add_u64 v[148:149], v[98:99], 0, v[70:71]
	v_lshl_add_u64 v[146:147], v[98:99], 0, v[72:73]
	global_load_dwordx4 v[84:87], v[40:41], off nt
	global_load_dwordx4 v[72:75], v[40:41], off offset:1024 nt
	global_load_dwordx4 v[68:71], v[40:41], off offset:3072 nt
	global_load_dwordx4 v[76:79], v[40:41], off offset:2048 nt
	global_load_dwordx4 v[56:59], v[80:81], off nt
	v_lshlrev_b64 v[36:37], 11, v[36:37]
	v_lshlrev_b64 v[38:39], 11, v[38:39]
	v_lshlrev_b64 v[42:43], 12, v[44:45]
	v_lshlrev_b64 v[82:83], 12, v[46:47]
	v_lshl_add_u64 v[166:167], v[100:101], 0, v[62:63]
	v_lshl_add_u64 v[164:165], v[102:103], 0, v[64:65]
	v_lshl_add_u64 v[162:163], v[104:105], 0, v[64:65]
	v_lshl_add_u64 v[154:155], v[100:101], 0, v[66:67]
	v_lshlrev_b64 v[64:65], 12, v[48:49]
	v_lshlrev_b64 v[66:67], 12, v[50:51]
	v_lshl_add_u64 v[126:127], v[100:101], 0, v[32:33]
	v_lshlrev_b64 v[32:33], 11, v[48:49]
	v_lshl_add_u64 v[118:119], v[100:101], 0, v[34:35]
	v_lshlrev_b64 v[34:35], 11, v[50:51]
	global_load_dwordx4 v[60:63], v[80:81], off offset:1024 nt
	global_load_dwordx4 v[52:55], v[80:81], off offset:2048 nt
	global_load_dwordx4 v[48:51], v[80:81], off offset:3072 nt
	v_lshlrev_b64 v[44:45], 11, v[44:45]
	v_lshlrev_b64 v[46:47], 11, v[46:47]
	v_lshl_add_u64 v[124:125], v[102:103], 0, v[36:37]
	v_lshl_add_u64 v[122:123], v[104:105], 0, v[36:37]
	v_lshl_add_u64 v[116:117], v[102:103], 0, v[38:39]
	v_lshl_add_u64 v[114:115], v[104:105], 0, v[38:39]
	v_lshl_add_u64 v[36:37], v[98:99], 0, v[42:43]
	v_lshl_add_u64 v[38:39], v[98:99], 0, v[82:83]
	v_lshl_add_u64 v[168:169], v[100:101], 0, v[44:45]
	v_lshl_add_u64 v[160:161], v[100:101], 0, v[46:47]
	v_lshl_add_u64 v[158:159], v[98:99], 0, v[64:65]
	v_lshl_add_u64 v[156:157], v[98:99], 0, v[66:67]
	v_lshl_add_u64 v[128:129], v[100:101], 0, v[32:33]
	v_lshl_add_u64 v[120:121], v[100:101], 0, v[34:35]
	global_load_dwordx4 v[92:95], v[36:37], off nt
	global_load_dwordx4 v[88:91], v[36:37], off offset:1024 nt
	global_load_dwordx4 v[64:67], v[36:37], off offset:3072 nt
	global_load_dwordx4 v[80:83], v[36:37], off offset:2048 nt
	global_load_dwordx4 v[44:47], v[38:39], off nt
	global_load_dwordx4 v[40:43], v[38:39], off offset:1024 nt
	global_load_dwordx4 v[32:35], v[38:39], off offset:3072 nt
	s_nop 0
	global_load_dwordx4 v[36:39], v[38:39], off offset:2048 nt
	v_add_u32_e32 v173, s26, v173
	v_cmp_lt_i32_e32 vcc, s41, v173
	s_or_b64 s[22:23], vcc, s[22:23]
	v_add_u32_e32 v180, s27, v180
	s_waitcnt vmcnt(21)
	v_pk_add_f32 v[132:133], v[132:133], 1.0 op_sel_hi:[1,0]
	v_pk_add_f32 v[184:185], v[130:131], 1.0 op_sel_hi:[1,0]
	s_waitcnt vmcnt(19)
	v_pk_add_f32 v[186:187], v[136:137], 1.0 op_sel_hi:[1,0]
	v_pk_add_f32 v[188:189], v[134:135], 1.0 op_sel_hi:[1,0]
	s_waitcnt vmcnt(17)
; __device__ __forceinline__ void pass_h_fold(const float* src, const float* g, const float* mod, bf16_t* H, bf16_t* HE, bf16_t* HO) {
;     ...
;         for (int j = 0; j < 4; ++j) { const f32x4 gg = ((const f32x4*)g)[lane + 64 * j], sc = ((const f32x4*)(mod + (size_t)b * NMOD + DM))[lane + 64 * j];
;             mul[j] = gg * (1.0f + sc); sh[j] = ((const f32x4*)(mod + (size_t)b * NMOD))[lane + 64 * j]; }
;     ...
;                 for (int j = 0; j < 4; ++j) { const f32x4 a = v[q][0][j], c = v[q][1][j]; t0 += (a[0] * a[0] + a[1] * a[1]) + (a[2] * a[2] + a[3] * a[3]); t1 += (c[0] * c[0] + c[1] * c[1]) + (c[2] * c[2] + c[3] * c[3]); }
	v_pk_add_f32 v[144:145], v[144:145], 1.0 op_sel_hi:[1,0]
	v_pk_add_f32 v[142:143], v[142:143], 1.0 op_sel_hi:[1,0]
	v_pk_add_f32 v[190:191], v[140:141], 1.0 op_sel_hi:[1,0]
	v_pk_add_f32 v[192:193], v[138:139], 1.0 op_sel_hi:[1,0]
	v_pk_mul_f32 v[130:131], v[2:3], v[132:133]
	v_pk_mul_f32 v[132:133], v[0:1], v[184:185]
	v_pk_mul_f32 v[134:135], v[6:7], v[144:145]
	v_pk_mul_f32 v[136:137], v[4:5], v[142:143]
	v_pk_mul_f32 v[138:139], v[10:11], v[186:187]
	v_pk_mul_f32 v[140:141], v[8:9], v[188:189]
	v_pk_mul_f32 v[142:143], v[14:15], v[190:191]
	v_pk_mul_f32 v[144:145], v[12:13], v[192:193]
	s_waitcnt vmcnt(15)
	v_pk_mul_f32 v[0:1], v[86:87], v[86:87]
	v_pk_mul_f32 v[2:3], v[84:85], v[84:85]
	s_waitcnt vmcnt(14)
	v_pk_mul_f32 v[4:5], v[74:75], v[74:75]
	v_pk_mul_f32 v[6:7], v[72:73], v[72:73]
	s_waitcnt vmcnt(12)
	v_mul_f32_e32 v8, v77, v77
	v_mul_f32_e32 v10, v79, v79
	s_waitcnt vmcnt(11)
	v_pk_mul_f32 v[12:13], v[58:59], v[58:59]
	v_pk_mul_f32 v[14:15], v[56:57], v[56:57]
	v_pk_mov_b32 v[192:193], v[2:3], v[0:1] op_sel:[1,0]
	v_mov_b32_e32 v3, v1
	v_pk_mov_b32 v[196:197], v[6:7], v[4:5] op_sel:[1,0]
	v_mov_b32_e32 v7, v5
	v_mul_f32_e32 v201, v70, v70
	v_mul_f32_e32 v203, v71, v71
	v_pk_fma_f32 v[8:9], v[76:77], v[76:77], v[8:9] op_sel_hi:[1,1,0]
	v_pk_fma_f32 v[10:11], v[78:79], v[78:79], v[10:11] op_sel_hi:[1,1,0]
	v_pk_mov_b32 v[204:205], v[14:15], v[12:13] op_sel:[1,0]
	s_waitcnt vmcnt(10)
	v_pk_mul_f32 v[184:185], v[62:63], v[62:63]
	v_pk_mul_f32 v[186:187], v[60:61], v[60:61]
	s_waitcnt vmcnt(9)
	v_mul_f32_e32 v188, v53, v53
	v_mul_f32_e32 v190, v55, v55
	s_waitcnt vmcnt(8)
	v_mul_f32_e32 v218, v50, v50
	v_mul_f32_e32 v219, v51, v51
	v_mov_b32_e32 v15, v13
	v_pk_mov_b32 v[208:209], v[186:187], v[184:185] op_sel:[1,0]
	v_mov_b32_e32 v187, v185
	v_pk_fma_f32 v[188:189], v[52:53], v[52:53], v[188:189] op_sel_hi:[1,1,0]
	s_waitcnt vmcnt(7)
	v_pk_mul_f32 v[0:1], v[94:95], v[94:95]
	v_pk_mul_f32 v[194:195], v[92:93], v[92:93]
	s_waitcnt vmcnt(6)
	v_pk_mul_f32 v[4:5], v[90:91], v[90:91]
	v_pk_mul_f32 v[198:199], v[88:89], v[88:89]
	s_waitcnt vmcnt(4)
	v_mul_f32_e32 v200, v81, v81
	s_waitcnt vmcnt(3)
	v_pk_mul_f32 v[12:13], v[46:47], v[46:47]
	v_pk_mul_f32 v[206:207], v[44:45], v[44:45]
	s_waitcnt vmcnt(2)
	v_pk_mul_f32 v[184:185], v[42:43], v[42:43]
	v_pk_mul_f32 v[210:211], v[40:41], v[40:41]
	v_pk_fma_f32 v[190:191], v[54:55], v[54:55], v[190:191] op_sel_hi:[1,1,0]
	v_pk_add_f32 v[2:3], v[192:193], v[2:3]
	v_pk_mov_b32 v[192:193], v[194:195], v[0:1] op_sel:[1,0]
	v_mov_b32_e32 v195, v1
	v_pk_add_f32 v[0:1], v[196:197], v[6:7]
	v_pk_mov_b32 v[6:7], v[198:199], v[4:5] op_sel:[1,0]
	v_mov_b32_e32 v199, v5
	v_mul_f32_e32 v213, v68, v68
	v_mul_f32_e32 v215, v69, v69
	v_mul_f32_e32 v202, v83, v83
	v_mov_b32_e32 v9, v201
	v_mov_b32_e32 v11, v203
	v_pk_fma_f32 v[4:5], v[80:81], v[80:81], v[200:201] op_sel_hi:[1,1,0]
	v_pk_add_f32 v[14:15], v[204:205], v[14:15]
	v_pk_mov_b32 v[200:201], v[206:207], v[12:13] op_sel:[1,0]
	v_mov_b32_e32 v207, v13
	v_pk_add_f32 v[12:13], v[208:209], v[186:187]
	v_pk_mov_b32 v[186:187], v[210:211], v[184:185] op_sel:[1,0]
	v_mov_b32_e32 v211, v185
	v_mov_b32_e32 v189, v218
	v_mov_b32_e32 v191, v219
	v_pk_add_f32 v[192:193], v[192:193], v[194:195]
	v_pk_add_f32 v[6:7], v[6:7], v[198:199]
	v_pk_add_f32 v[2:3], v[2:3], v[2:3] op_sel:[0,1] op_sel_hi:[1,0]
	v_pk_add_f32 v[0:1], v[0:1], v[0:1] op_sel:[0,1] op_sel_hi:[1,0]
	v_mul_f32_e32 v216, v48, v48
	v_mul_f32_e32 v217, v49, v49
	v_mul_f32_e32 v220, v64, v64
	v_mul_f32_e32 v221, v65, v65
	v_mul_f32_e32 v222, v66, v66
	v_mul_f32_e32 v223, v67, v67
	v_pk_fma_f32 v[196:197], v[82:83], v[82:83], v[202:203] op_sel_hi:[1,1,0]
	v_pk_add_f32 v[8:9], v[8:9], v[10:11]
	v_pk_add_f32 v[10:11], v[200:201], v[206:207]
	v_pk_add_f32 v[186:187], v[186:187], v[210:211]
	v_pk_add_f32 v[14:15], v[14:15], v[14:15] op_sel:[0,1] op_sel_hi:[1,0]
	v_pk_add_f32 v[12:13], v[12:13], v[12:13] op_sel:[0,1] op_sel_hi:[1,0]
	v_pk_add_f32 v[188:189], v[188:189], v[190:191]
	v_mov_b32_e32 v3, v213
	v_mov_b32_e32 v1, v215
	v_pk_add_f32 v[190:191], v[192:193], v[192:193] op_sel:[0,1] op_sel_hi:[1,0]
	v_pk_add_f32 v[6:7], v[6:7], v[6:7] op_sel:[0,1] op_sel_hi:[1,0]
	s_waitcnt vmcnt(1)
	v_mul_f32_e32 v224, v32, v32
	v_mul_f32_e32 v225, v33, v33
	s_waitcnt vmcnt(0)
	v_mul_f32_e32 v212, v37, v37
	v_mul_f32_e32 v214, v39, v39
	v_mov_b32_e32 v5, v222
	v_mov_b32_e32 v197, v223
	v_mov_b32_e32 v15, v216
	v_mov_b32_e32 v13, v217
	v_pk_add_f32 v[10:11], v[10:11], v[10:11] op_sel:[0,1] op_sel_hi:[1,0]
	v_pk_add_f32 v[186:187], v[186:187], v[186:187] op_sel:[0,1] op_sel_hi:[1,0]
	v_pk_add_f32 v[0:1], v[2:3], v[0:1]
	v_mov_b32_e32 v191, v220
	v_mov_b32_e32 v7, v221
	v_mul_f32_e32 v226, v34, v34
	v_mul_f32_e32 v227, v35, v35
	v_pk_fma_f32 v[184:185], v[36:37], v[36:37], v[212:213] op_sel_hi:[1,1,0]
	v_pk_fma_f32 v[202:203], v[38:39], v[38:39], v[214:215] op_sel_hi:[1,1,0]
	v_pk_add_f32 v[4:5], v[4:5], v[196:197]
	v_pk_add_f32 v[2:3], v[14:15], v[12:13]
	v_mov_b32_e32 v11, v224
	v_mov_b32_e32 v187, v225
	v_pk_add_f32 v[0:1], v[0:1], v[8:9]
	v_pk_add_f32 v[6:7], v[190:191], v[6:7]
	v_mov_b32_e32 v185, v226
	v_mov_b32_e32 v203, v227
	v_pk_add_f32 v[2:3], v[2:3], v[188:189]
	v_pk_add_f32 v[8:9], v[10:11], v[186:187]
	v_add_f32_e32 v10, v0, v1
	v_pk_add_f32 v[0:1], v[6:7], v[4:5]
	v_pk_add_f32 v[184:185], v[184:185], v[202:203]
	v_add_f32_e32 v4, v2, v3
	v_add_f32_e32 v0, v0, v1
	ds_bpermute_b32 v1, v174, v10
	v_pk_add_f32 v[2:3], v[8:9], v[184:185]
	ds_bpermute_b32 v5, v174, v4
	v_add_f32_e32 v2, v2, v3
	ds_bpermute_b32 v3, v174, v0
	ds_bpermute_b32 v6, v174, v2
	s_waitcnt lgkmcnt(3)
	v_add_f32_e32 v1, v10, v1
	s_waitcnt lgkmcnt(2)
; __device__ __forceinline__ void pass_h_fold(const float* src, const float* g, const float* mod, bf16_t* H, bf16_t* HE, bf16_t* HO) {
;     ...
;                 t0 = wave_sum(t0); t1 = wave_sum(t1);
;                 const float r0 = 1.0f / sqrtf(t0 * (1.0f / DM) + EPS), r1 = 1.0f / sqrtf(t1 * (1.0f / DM) + EPS);
;                 u32x2* o0 = (u32x2*)(H + (size_t)(b * SEQ + s) * DM) + lane; u32x2* o1 = (u32x2*)(H + (size_t)(b * SEQ + pr) * DM) + lane;
;                 u32x2* oe = (u32x2*)(HE + (size_t)(b * 1024 + s) * DM) + lane; u32x2* oo = (u32x2*)(HO + (size_t)(b * 1024 + s) * DM) + lane;
; #pragma unroll
;                 for (int j = 0; j < 4; ++j) { const f32x4 h0 = (v[q][0][j] * r0) * mul[j] + sh[j], h1 = (v[q][1][j] * r1) * mul[j] + sh[j];
	v_add_f32_e32 v4, v4, v5
	ds_bpermute_b32 v5, v175, v1
	s_waitcnt lgkmcnt(2)
	v_add_f32_e32 v0, v0, v3
	ds_bpermute_b32 v3, v175, v4
	s_waitcnt lgkmcnt(2)
	v_add_f32_e32 v2, v2, v6
	ds_bpermute_b32 v6, v175, v0
	ds_bpermute_b32 v7, v175, v2
	s_waitcnt lgkmcnt(3)
	v_add_f32_e32 v1, v1, v5
	s_waitcnt lgkmcnt(2)
	v_add_f32_e32 v3, v4, v3
	ds_bpermute_b32 v4, v176, v1
	s_waitcnt lgkmcnt(2)
	v_add_f32_e32 v0, v0, v6
	ds_bpermute_b32 v5, v176, v3
	s_waitcnt lgkmcnt(2)
	v_add_f32_e32 v2, v2, v7
	ds_bpermute_b32 v6, v176, v0
	ds_bpermute_b32 v7, v176, v2
	s_waitcnt lgkmcnt(3)
	v_add_f32_e32 v1, v1, v4
	s_waitcnt lgkmcnt(2)
	v_add_f32_e32 v3, v3, v5
	ds_bpermute_b32 v4, v177, v1
	s_waitcnt lgkmcnt(2)
	v_add_f32_e32 v0, v0, v6
	ds_bpermute_b32 v5, v177, v3
	s_waitcnt lgkmcnt(2)
	v_add_f32_e32 v2, v2, v7
	ds_bpermute_b32 v6, v177, v0
	ds_bpermute_b32 v7, v177, v2
	s_waitcnt lgkmcnt(3)
	v_add_f32_e32 v1, v1, v4
	s_waitcnt lgkmcnt(2)
	v_add_f32_e32 v3, v3, v5
	ds_bpermute_b32 v4, v178, v1
	s_waitcnt lgkmcnt(2)
	v_add_f32_e32 v0, v0, v6
	ds_bpermute_b32 v5, v178, v3
	s_waitcnt lgkmcnt(2)
	v_add_f32_e32 v2, v2, v7
	ds_bpermute_b32 v6, v178, v0
	ds_bpermute_b32 v7, v178, v2
	s_waitcnt lgkmcnt(3)
	v_add_f32_e32 v1, v1, v4
	s_waitcnt lgkmcnt(2)
	v_add_f32_e32 v3, v3, v5
	ds_bpermute_b32 v4, v179, v1
	s_waitcnt lgkmcnt(2)
	v_add_f32_e32 v0, v0, v6
	ds_bpermute_b32 v5, v179, v3
	s_waitcnt lgkmcnt(2)
	v_add_f32_e32 v2, v2, v7
	ds_bpermute_b32 v6, v179, v0
	ds_bpermute_b32 v7, v179, v2
	s_waitcnt lgkmcnt(3)
	v_add_f32_e32 v1, v1, v4
	s_waitcnt lgkmcnt(2)
	v_add_f32_e32 v3, v3, v5
	v_fmamk_f32 v1, v1, 0x3a800000, v182
	s_waitcnt lgkmcnt(1)
	v_add_f32_e32 v0, v0, v6
	v_fmamk_f32 v3, v3, 0x3a800000, v182
	v_mul_f32_e32 v4, 0x4f800000, v1
	v_cmp_gt_f32_e64 s[6:7], s40, v1
	s_waitcnt lgkmcnt(0)
	v_add_f32_e32 v2, v2, v7
	v_fmamk_f32 v0, v0, 0x3a800000, v182
	v_mul_f32_e32 v5, 0x4f800000, v3
	v_cmp_gt_f32_e32 vcc, s40, v3
	v_cndmask_b32_e64 v1, v1, v4, s[6:7]
	v_fmamk_f32 v2, v2, 0x3a800000, v182
	v_mul_f32_e32 v4, 0x4f800000, v0
	v_cmp_gt_f32_e64 s[8:9], s40, v0
	v_cndmask_b32_e32 v3, v3, v5, vcc
	v_sqrt_f32_e32 v6, v1
	v_mul_f32_e32 v5, 0x4f800000, v2
	v_cmp_gt_f32_e64 s[12:13], s40, v2
	v_cndmask_b32_e64 v0, v0, v4, s[8:9]
	v_sqrt_f32_e32 v4, v3
	v_cndmask_b32_e64 v2, v2, v5, s[12:13]
	v_sqrt_f32_e32 v5, v0
	v_sqrt_f32_e32 v7, v2
	v_add_u32_e32 v8, -1, v6
	v_add_u32_e32 v9, 1, v6
	v_add_u32_e32 v10, -1, v4
	v_fma_f32 v12, -v8, v6, v1
	v_add_u32_e32 v11, 1, v4
	v_fma_f32 v13, -v9, v6, v1
	v_add_u32_e32 v14, -1, v5
	v_fma_f32 v184, -v10, v4, v3
	v_cmp_ge_f32_e64 s[14:15], 0, v12
	v_add_u32_e32 v15, 1, v5
	v_fma_f32 v185, -v11, v4, v3
	v_add_u32_e32 v186, -1, v7
	v_cndmask_b32_e64 v6, v6, v8, s[14:15]
	v_fma_f32 v8, -v14, v5, v0
	v_cmp_ge_f32_e64 s[14:15], 0, v184
	v_cmp_lt_f32_e64 s[16:17], 0, v13
	v_add_u32_e32 v187, 1, v7
	v_fma_f32 v12, -v15, v5, v0
	v_cndmask_b32_e64 v4, v4, v10, s[14:15]
	v_cmp_lt_f32_e64 s[14:15], 0, v185
	v_fma_f32 v10, -v186, v7, v2
	v_cndmask_b32_e64 v6, v6, v9, s[16:17]
	v_cmp_ge_f32_e64 s[16:17], 0, v8
	v_fma_f32 v184, -v187, v7, v2
	v_cndmask_b32_e64 v4, v4, v11, s[14:15]
	v_cndmask_b32_e64 v5, v5, v14, s[16:17]
	v_cmp_lt_f32_e64 s[16:17], 0, v12
	v_cmp_ge_f32_e64 s[14:15], 0, v10
	v_mul_f32_e32 v8, 0x37800000, v6
	v_cndmask_b32_e64 v5, v5, v15, s[16:17]
	v_cndmask_b32_e64 v7, v7, v186, s[14:15]
	v_cmp_lt_f32_e64 s[14:15], 0, v184
	v_mul_f32_e32 v9, 0x37800000, v4
	v_cndmask_b32_e64 v6, v6, v8, s[6:7]
	v_cndmask_b32_e64 v7, v7, v187, s[14:15]
	v_mul_f32_e32 v8, 0x37800000, v5
	v_cmp_class_f32_e64 s[6:7], v1, v183
	v_cndmask_b32_e32 v4, v4, v9, vcc
	v_cmp_class_f32_e32 vcc, v3, v183
	v_mul_f32_e32 v9, 0x37800000, v7
	v_cndmask_b32_e64 v1, v6, v1, s[6:7]
	v_cndmask_b32_e64 v5, v5, v8, s[8:9]
	v_cmp_class_f32_e64 s[6:7], v0, v183
	v_cndmask_b32_e32 v184, v4, v3, vcc
	v_cndmask_b32_e64 v3, v7, v9, s[12:13]
	v_cmp_class_f32_e32 vcc, v2, v183
	v_div_scale_f32 v4, s[8:9], v1, v1, 1.0
	v_cndmask_b32_e64 v5, v5, v0, s[6:7]
	v_div_scale_f32 v0, s[6:7], v184, v184, 1.0
	v_cndmask_b32_e32 v185, v3, v2, vcc
	v_rcp_f32_e32 v2, v4
	v_div_scale_f32 v3, s[10:11], v5, v5, 1.0
	v_rcp_f32_e32 v186, v0
	v_div_scale_f32 v9, s[10:11], v185, v185, 1.0
	v_rcp_f32_e32 v11, v3
	v_rcp_f32_e32 v187, v9
	v_fma_f32 v12, -v4, v2, 1.0
	v_div_scale_f32 v6, s[8:9], 1.0, v1, 1.0
	v_fma_f32 v13, -v0, v186, 1.0
	v_fmac_f32_e32 v2, v12, v2
	v_fma_f32 v12, -v3, v11, 1.0
	v_div_scale_f32 v7, s[6:7], 1.0, v184, 1.0
	v_div_scale_f32 v8, s[12:13], 1.0, v5, 1.0
	v_fmac_f32_e32 v186, v13, v186
	v_fma_f32 v13, -v9, v187, 1.0
	v_mul_f32_e32 v14, v6, v2
	v_fmac_f32_e32 v11, v12, v11
	v_mul_f32_e32 v188, v7, v186
	v_fmac_f32_e32 v187, v13, v187
	v_fma_f32 v12, -v4, v14, v6
	v_mul_f32_e32 v13, v8, v11
	v_fma_f32 v15, -v0, v188, v7
	v_fmac_f32_e32 v14, v12, v2
	v_fma_f32 v12, -v3, v13, v8
	v_div_scale_f32 v10, s[14:15], 1.0, v185, 1.0
	v_fmac_f32_e32 v188, v15, v186
	v_fma_f32 v4, -v4, v14, v6
	v_fmac_f32_e32 v13, v12, v11
	s_mov_b64 vcc, s[8:9]
	v_mul_f32_e32 v189, v10, v187
	v_fma_f32 v190, -v0, v188, v7
	v_div_fmas_f32 v0, v4, v2, v14
	v_fma_f32 v2, -v3, v13, v8
	s_mov_b64 vcc, s[12:13]
	v_fma_f32 v15, -v9, v189, v10
	v_div_fixup_f32 v0, v0, v1, 1.0
	v_div_fmas_f32 v1, v2, v11, v13
	v_fmac_f32_e32 v189, v15, v187
	v_div_fixup_f32 v2, v1, v5, 1.0
	s_mov_b64 vcc, s[6:7]
	v_fma_f32 v191, -v9, v189, v10
	v_pk_mul_f32 v[4:5], v[84:85], v[0:1] op_sel_hi:[1,0]
	v_pk_mul_f32 v[6:7], v[86:87], v[0:1] op_sel_hi:[1,0]
	v_pk_mul_f32 v[8:9], v[72:73], v[0:1] op_sel_hi:[1,0]
	v_pk_mul_f32 v[10:11], v[74:75], v[0:1] op_sel_hi:[1,0]
	v_pk_mul_f32 v[12:13], v[76:77], v[0:1] op_sel_hi:[1,0]
; __device__ __forceinline__ unsigned cvt_pk_bf16(float lo, float hi) { unsigned r; asm volatile("v_cvt_pk_bf16_f32 %0, %1, %2" : "=v"(r) : "v"(lo), "v"(hi)); return r; }
; __device__ __forceinline__ void pass_h_fold(const float* src, const float* g, const float* mod, bf16_t* H, bf16_t* HE, bf16_t* HO) {
;     ...
;                 u32x2* o0 = (u32x2*)(H + (size_t)(b * SEQ + s) * DM) + lane; u32x2* o1 = (u32x2*)(H + (size_t)(b * SEQ + pr) * DM) + lane;
;                 u32x2* oe = (u32x2*)(HE + (size_t)(b * 1024 + s) * DM) + lane; u32x2* oo = (u32x2*)(HO + (size_t)(b * 1024 + s) * DM) + lane;
; #pragma unroll
;                 for (int j = 0; j < 4; ++j) { const f32x4 h0 = (v[q][0][j] * r0) * mul[j] + sh[j], h1 = (v[q][1][j] * r1) * mul[j] + sh[j];
;                     u32x2 w; w.x = cvt_pk_bf16(h0[0], h0[1]); w.y = cvt_pk_bf16(h0[2], h0[3]); o0[64 * j] = w;
;                     w.x = cvt_pk_bf16(h1[0], h1[1]); w.y = cvt_pk_bf16(h1[2], h1[3]); o1[64 * j] = w;
;                     const f32x4 e = (s == 0) ? h0 : h0 + h1, o = (s == 0) ? (f32x4){0.f, 0.f, 0.f, 0.f} : h0 - h1;
;                     w.x = cvt_pk_bf16(e[0], e[1]); w.y = cvt_pk_bf16(e[2], e[3]); oe[64 * j] = w;
;                     w.x = cvt_pk_bf16(o[0], o[1]); w.y = cvt_pk_bf16(o[2], o[3]); oo[64 * j] = w; } }
	v_pk_mul_f32 v[14:15], v[78:79], v[0:1] op_sel_hi:[1,0]
	v_pk_mul_f32 v[68:69], v[68:69], v[0:1] op_sel_hi:[1,0]
	v_pk_mul_f32 v[0:1], v[70:71], v[0:1] op_sel_hi:[1,0]
	v_div_fmas_f32 v84, v190, v186, v188
	v_pk_mul_f32 v[70:71], v[92:93], v[2:3] op_sel_hi:[1,0]
	s_mov_b64 vcc, s[14:15]
	v_pk_fma_f32 v[4:5], v[132:133], v[4:5], v[28:29]
	v_pk_mul_f32 v[72:73], v[94:95], v[2:3] op_sel_hi:[1,0]
	v_pk_mul_f32 v[74:75], v[88:89], v[2:3] op_sel_hi:[1,0]
	v_pk_mul_f32 v[76:77], v[90:91], v[2:3] op_sel_hi:[1,0]
	v_pk_mul_f32 v[78:79], v[80:81], v[2:3] op_sel_hi:[1,0]
	v_pk_mul_f32 v[80:81], v[82:83], v[2:3] op_sel_hi:[1,0]
	v_pk_mul_f32 v[64:65], v[64:65], v[2:3] op_sel_hi:[1,0]
	v_pk_mul_f32 v[2:3], v[66:67], v[2:3] op_sel_hi:[1,0]
	v_div_fmas_f32 v67, v191, v187, v189
	v_pk_fma_f32 v[70:71], v[132:133], v[70:71], v[28:29]
	v_pk_fma_f32 v[6:7], v[130:131], v[6:7], v[30:31]
	v_div_fixup_f32 v66, v84, v184, 1.0
	v_pk_fma_f32 v[72:73], v[130:131], v[72:73], v[30:31]
	v_cvt_pk_bf16_f32 v82, v4, v5
	v_cvt_pk_bf16_f32 v83, v6, v7
	v_div_fixup_f32 v84, v67, v185, 1.0
	v_sub_f32_e32 v85, v5, v71
	v_pk_fma_f32 v[8:9], v[136:137], v[8:9], v[20:21]
	v_pk_fma_f32 v[74:75], v[136:137], v[74:75], v[20:21]
	v_pk_mul_f32 v[56:57], v[56:57], v[66:67] op_sel_hi:[1,0]
	v_pk_mul_f32 v[58:59], v[58:59], v[66:67] op_sel_hi:[1,0]
	v_pk_mul_f32 v[60:61], v[60:61], v[66:67] op_sel_hi:[1,0]
	v_pk_mul_f32 v[62:63], v[62:63], v[66:67] op_sel_hi:[1,0]
	v_pk_mul_f32 v[52:53], v[52:53], v[66:67] op_sel_hi:[1,0]
	v_pk_mul_f32 v[54:55], v[54:55], v[66:67] op_sel_hi:[1,0]
	v_pk_mul_f32 v[48:49], v[48:49], v[66:67] op_sel_hi:[1,0]
	v_pk_mul_f32 v[50:51], v[50:51], v[66:67] op_sel_hi:[1,0]
	global_store_dwordx2 v[166:167], v[82:83], off
	v_cvt_pk_bf16_f32 v66, v70, v71
	v_cvt_pk_bf16_f32 v67, v72, v73
	v_pk_add_f32 v[82:83], v[4:5], v[70:71]
	v_pk_add_f32 v[86:87], v[6:7], v[72:73]
	v_pk_mul_f32 v[44:45], v[44:45], v[84:85] op_sel_hi:[1,0]
	v_sub_f32_e32 v184, v4, v70
	v_sub_f32_e32 v185, v7, v73
	v_sub_f32_e32 v186, v6, v72
	v_pk_add_f32 v[70:71], v[8:9], v[74:75]
	global_store_dwordx2 v[168:169], v[66:67], off
	v_cndmask_b32_e64 v66, v86, v6, s[4:5]
	v_cndmask_b32_e64 v67, v87, v7, s[4:5]
	v_cndmask_b32_e64 v82, v82, v4, s[4:5]
	v_cndmask_b32_e64 v83, v83, v5, s[4:5]
	v_pk_fma_f32 v[6:7], v[132:133], v[44:45], v[28:29]
	v_cvt_pk_bf16_f32 v44, v82, v83
	v_cvt_pk_bf16_f32 v45, v66, v67
	v_pk_fma_f32 v[10:11], v[134:135], v[10:11], v[22:23]
	v_pk_fma_f32 v[76:77], v[134:135], v[76:77], v[22:23]
	v_sub_f32_e32 v187, v9, v75
	v_sub_f32_e32 v188, v8, v74
	v_cndmask_b32_e64 v186, v186, 0, s[4:5]
	v_cndmask_b32_e64 v185, v185, 0, s[4:5]
	v_cndmask_b32_e64 v184, v184, 0, s[4:5]
	v_cndmask_b32_e64 v199, v85, 0, s[4:5]
	v_cndmask_b32_e64 v202, v70, v8, s[4:5]
	v_cndmask_b32_e64 v203, v71, v9, s[4:5]
	global_store_dwordx2 v[164:165], v[44:45], off
	v_cvt_pk_bf16_f32 v44, v184, v199
	v_cvt_pk_bf16_f32 v45, v186, v185
	global_store_dwordx2 v[162:163], v[44:45], off
	v_cvt_pk_bf16_f32 v8, v8, v9
	v_cvt_pk_bf16_f32 v9, v10, v11
	v_pk_add_f32 v[72:73], v[10:11], v[76:77]
	global_store_dwordx2 v[166:167], v[8:9], off offset:512
	v_cvt_pk_bf16_f32 v8, v74, v75
	v_cvt_pk_bf16_f32 v9, v76, v77
	v_sub_f32_e32 v189, v11, v77
	v_sub_f32_e32 v190, v10, v76
	v_cndmask_b32_e64 v200, v72, v10, s[4:5]
	v_cndmask_b32_e64 v201, v73, v11, s[4:5]
	global_store_dwordx2 v[168:169], v[8:9], off offset:512
	v_cvt_pk_bf16_f32 v8, v202, v203
	v_cvt_pk_bf16_f32 v9, v200, v201
	v_cndmask_b32_e64 v190, v190, 0, s[4:5]
	v_cndmask_b32_e64 v189, v189, 0, s[4:5]
	v_cndmask_b32_e64 v188, v188, 0, s[4:5]
	v_cndmask_b32_e64 v187, v187, 0, s[4:5]
	global_store_dwordx2 v[164:165], v[8:9], off offset:512
	v_cvt_pk_bf16_f32 v8, v188, v187
	v_cvt_pk_bf16_f32 v9, v190, v189
	v_pk_fma_f32 v[14:15], v[138:139], v[14:15], v[18:19]
	v_pk_fma_f32 v[12:13], v[140:141], v[12:13], v[16:17]
	v_pk_fma_f32 v[80:81], v[138:139], v[80:81], v[18:19]
	v_pk_fma_f32 v[78:79], v[140:141], v[78:79], v[16:17]
	global_store_dwordx2 v[162:163], v[8:9], off offset:512
	v_cvt_pk_bf16_f32 v8, v12, v13
	v_cvt_pk_bf16_f32 v9, v14, v15
	v_pk_add_f32 v[88:89], v[12:13], v[78:79]
	v_pk_add_f32 v[90:91], v[14:15], v[80:81]
	global_store_dwordx2 v[166:167], v[8:9], off offset:1024
	v_cvt_pk_bf16_f32 v8, v78, v79
	v_cvt_pk_bf16_f32 v9, v80, v81
	v_pk_fma_f32 v[0:1], v[142:143], v[0:1], v[26:27]
	v_pk_fma_f32 v[2:3], v[142:143], v[2:3], v[26:27]
	v_sub_f32_e32 v191, v13, v79
	v_sub_f32_e32 v192, v12, v78
	v_sub_f32_e32 v193, v15, v81
	v_sub_f32_e32 v194, v14, v80
	v_cndmask_b32_e64 v90, v90, v14, s[4:5]
	v_cndmask_b32_e64 v91, v91, v15, s[4:5]
	v_cndmask_b32_e64 v204, v88, v12, s[4:5]
	v_cndmask_b32_e64 v205, v89, v13, s[4:5]
	global_store_dwordx2 v[168:169], v[8:9], off offset:1024
	v_cvt_pk_bf16_f32 v8, v204, v205
	v_cvt_pk_bf16_f32 v9, v90, v91
	v_pk_fma_f32 v[68:69], v[144:145], v[68:69], v[24:25]
	v_pk_fma_f32 v[64:65], v[144:145], v[64:65], v[24:25]
	v_pk_add_f32 v[94:95], v[0:1], v[2:3]
	v_cndmask_b32_e64 v194, v194, 0, s[4:5]
	v_cndmask_b32_e64 v193, v193, 0, s[4:5]
	v_cndmask_b32_e64 v192, v192, 0, s[4:5]
	v_cndmask_b32_e64 v191, v191, 0, s[4:5]
	global_store_dwordx2 v[164:165], v[8:9], off offset:1024
	v_cvt_pk_bf16_f32 v8, v192, v191
	v_cvt_pk_bf16_f32 v9, v194, v193
	v_pk_add_f32 v[92:93], v[68:69], v[64:65]
	v_sub_f32_e32 v197, v1, v3
	v_sub_f32_e32 v198, v0, v2
	v_cndmask_b32_e64 v94, v94, v0, s[4:5]
	v_cndmask_b32_e64 v95, v95, v1, s[4:5]
	global_store_dwordx2 v[162:163], v[8:9], off offset:1024
	v_cvt_pk_bf16_f32 v8, v68, v69
	v_cvt_pk_bf16_f32 v9, v0, v1
	global_store_dwordx2 v[166:167], v[8:9], off offset:1536
	v_cvt_pk_bf16_f32 v0, v64, v65
; __device__ __forceinline__ unsigned cvt_pk_bf16(float lo, float hi) { unsigned r; asm volatile("v_cvt_pk_bf16_f32 %0, %1, %2" : "=v"(r) : "v"(lo), "v"(hi)); return r; }
; __device__ __forceinline__ void pass_h_fold(const float* src, const float* g, const float* mod, bf16_t* H, bf16_t* HE, bf16_t* HO) {
;     ...
;             for (int q = 0; q < 2; ++q) { const int s = sb + half * 2 + q, pr = (s == 0) ? SEQ / 2 : SEQ - s;
;                 const f32x4* x0 = (const f32x4*)(src + (size_t)(b * SEQ + s) * DM) + lane; const f32x4* x1 = (const f32x4*)(src + (size_t)(b * SEQ + pr) * DM) + lane;
; #pragma unroll
;                 for (int j = 0; j < 4; ++j) { v[q][0][j] = x0[64 * j]; v[q][1][j] = x1[64 * j]; } }
; #pragma unroll
;             for (int q = 0; q < 2; ++q) { const int s = sb + half * 2 + q, pr = (s == 0) ? SEQ / 2 : SEQ - s;
;                 float t0 = 0.f, t1 = 0.f;
; #pragma unroll
;                 for (int j = 0; j < 4; ++j) { const f32x4 a = v[q][0][j], c = v[q][1][j]; t0 += (a[0] * a[0] + a[1] * a[1]) + (a[2] * a[2] + a[3] * a[3]); t1 += (c[0] * c[0] + c[1] * c[1]) + (c[2] * c[2] + c[3] * c[3]); }
;                 t0 = wave_sum(t0); t1 = wave_sum(t1);
;                 const float r0 = 1.0f / sqrtf(t0 * (1.0f / DM) + EPS), r1 = 1.0f / sqrtf(t1 * (1.0f / DM) + EPS);
;                 u32x2* o0 = (u32x2*)(H + (size_t)(b * SEQ + s) * DM) + lane; u32x2* o1 = (u32x2*)(H + (size_t)(b * SEQ + pr) * DM) + lane;
;                 u32x2* oe = (u32x2*)(HE + (size_t)(b * 1024 + s) * DM) + lane; u32x2* oo = (u32x2*)(HO + (size_t)(b * 1024 + s) * DM) + lane;
; #pragma unroll
;                 for (int j = 0; j < 4; ++j) { const f32x4 h0 = (v[q][0][j] * r0) * mul[j] + sh[j], h1 = (v[q][1][j] * r1) * mul[j] + sh[j];
;                     u32x2 w; w.x = cvt_pk_bf16(h0[0], h0[1]); w.y = cvt_pk_bf16(h0[2], h0[3]); o0[64 * j] = w;
;                     w.x = cvt_pk_bf16(h1[0], h1[1]); w.y = cvt_pk_bf16(h1[2], h1[3]); o1[64 * j] = w;
;                     const f32x4 e = (s == 0) ? h0 : h0 + h1, o = (s == 0) ? (f32x4){0.f, 0.f, 0.f, 0.f} : h0 - h1;
;                     w.x = cvt_pk_bf16(e[0], e[1]); w.y = cvt_pk_bf16(e[2], e[3]); oe[64 * j] = w;
;                     w.x = cvt_pk_bf16(o[0], o[1]); w.y = cvt_pk_bf16(o[2], o[3]); oo[64 * j] = w; } }
	v_cvt_pk_bf16_f32 v1, v2, v3
	v_sub_f32_e32 v195, v69, v65
	v_sub_f32_e32 v196, v68, v64
	v_cndmask_b32_e64 v92, v92, v68, s[4:5]
	v_cndmask_b32_e64 v93, v93, v69, s[4:5]
	global_store_dwordx2 v[168:169], v[0:1], off offset:1536
	v_cvt_pk_bf16_f32 v0, v92, v93
	v_cvt_pk_bf16_f32 v1, v94, v95
	v_cndmask_b32_e64 v198, v198, 0, s[4:5]
	v_cndmask_b32_e64 v197, v197, 0, s[4:5]
	v_cndmask_b32_e64 v196, v196, 0, s[4:5]
	v_cndmask_b32_e64 v195, v195, 0, s[4:5]
	global_store_dwordx2 v[164:165], v[0:1], off offset:1536
	v_cvt_pk_bf16_f32 v0, v196, v195
	v_cvt_pk_bf16_f32 v1, v198, v197
	v_pk_fma_f32 v[58:59], v[130:131], v[58:59], v[30:31]
	v_pk_fma_f32 v[56:57], v[132:133], v[56:57], v[28:29]
	v_pk_mul_f32 v[46:47], v[46:47], v[84:85] op_sel_hi:[1,0]
	global_store_dwordx2 v[162:163], v[0:1], off offset:1536
	v_cvt_pk_bf16_f32 v0, v56, v57
	v_cvt_pk_bf16_f32 v1, v58, v59
	v_pk_fma_f32 v[4:5], v[130:131], v[46:47], v[30:31]
	global_store_dwordx2 v[154:155], v[0:1], off
	v_cvt_pk_bf16_f32 v0, v6, v7
	v_cvt_pk_bf16_f32 v1, v4, v5
	v_pk_add_f32 v[46:47], v[58:59], v[4:5]
	v_pk_add_f32 v[66:67], v[56:57], v[6:7]
	global_store_dwordx2 v[160:161], v[0:1], off
	v_cvt_pk_bf16_f32 v0, v66, v67
	v_cvt_pk_bf16_f32 v1, v46, v47
	v_sub_f32_e32 v206, v58, v4
	v_sub_f32_e32 v207, v59, v5
	v_sub_f32_e32 v208, v56, v6
	v_sub_f32_e32 v209, v57, v7
	global_store_dwordx2 v[152:153], v[0:1], off
	v_cvt_pk_bf16_f32 v0, v208, v209
	v_cvt_pk_bf16_f32 v1, v206, v207
	v_pk_fma_f32 v[62:63], v[134:135], v[62:63], v[22:23]
	v_pk_fma_f32 v[60:61], v[136:137], v[60:61], v[20:21]
	v_pk_mul_f32 v[40:41], v[40:41], v[84:85] op_sel_hi:[1,0]
	v_pk_mul_f32 v[42:43], v[42:43], v[84:85] op_sel_hi:[1,0]
	global_store_dwordx2 v[150:151], v[0:1], off
	v_cvt_pk_bf16_f32 v0, v60, v61
	v_cvt_pk_bf16_f32 v1, v62, v63
	v_pk_fma_f32 v[42:43], v[134:135], v[42:43], v[22:23]
	v_pk_fma_f32 v[40:41], v[136:137], v[40:41], v[20:21]
	global_store_dwordx2 v[154:155], v[0:1], off offset:512
	v_cvt_pk_bf16_f32 v0, v40, v41
	v_cvt_pk_bf16_f32 v1, v42, v43
	v_pk_add_f32 v[70:71], v[62:63], v[42:43]
	v_pk_add_f32 v[72:73], v[60:61], v[40:41]
	global_store_dwordx2 v[160:161], v[0:1], off offset:512
	v_cvt_pk_bf16_f32 v0, v72, v73
	v_cvt_pk_bf16_f32 v1, v70, v71
	v_sub_f32_e32 v210, v62, v42
	v_sub_f32_e32 v211, v63, v43
	v_sub_f32_e32 v212, v60, v40
	v_sub_f32_e32 v213, v61, v41
	global_store_dwordx2 v[152:153], v[0:1], off offset:512
	v_cvt_pk_bf16_f32 v0, v212, v213
	v_cvt_pk_bf16_f32 v1, v210, v211
	v_pk_fma_f32 v[54:55], v[138:139], v[54:55], v[18:19]
	v_pk_fma_f32 v[52:53], v[140:141], v[52:53], v[16:17]
	v_pk_mul_f32 v[36:37], v[36:37], v[84:85] op_sel_hi:[1,0]
	v_pk_mul_f32 v[38:39], v[38:39], v[84:85] op_sel_hi:[1,0]
	global_store_dwordx2 v[150:151], v[0:1], off offset:512
	v_cvt_pk_bf16_f32 v0, v52, v53
	v_cvt_pk_bf16_f32 v1, v54, v55
	v_pk_fma_f32 v[38:39], v[138:139], v[38:39], v[18:19]
	v_pk_fma_f32 v[36:37], v[140:141], v[36:37], v[16:17]
	global_store_dwordx2 v[154:155], v[0:1], off offset:1024
	v_cvt_pk_bf16_f32 v0, v36, v37
	v_cvt_pk_bf16_f32 v1, v38, v39
	v_pk_mul_f32 v[32:33], v[32:33], v[84:85] op_sel_hi:[1,0]
	v_pk_mul_f32 v[34:35], v[34:35], v[84:85] op_sel_hi:[1,0]
	v_pk_add_f32 v[82:83], v[54:55], v[38:39]
	v_pk_add_f32 v[84:85], v[52:53], v[36:37]
	global_store_dwordx2 v[160:161], v[0:1], off offset:1024
	v_cvt_pk_bf16_f32 v0, v84, v85
	v_cvt_pk_bf16_f32 v1, v82, v83
	v_sub_f32_e32 v214, v54, v38
	v_sub_f32_e32 v215, v55, v39
	v_sub_f32_e32 v216, v52, v36
	v_sub_f32_e32 v217, v53, v37
	global_store_dwordx2 v[152:153], v[0:1], off offset:1024
	v_cvt_pk_bf16_f32 v0, v216, v217
	v_cvt_pk_bf16_f32 v1, v214, v215
	v_pk_fma_f32 v[50:51], v[142:143], v[50:51], v[26:27]
	v_pk_fma_f32 v[48:49], v[144:145], v[48:49], v[24:25]
	global_store_dwordx2 v[150:151], v[0:1], off offset:1024
	v_cvt_pk_bf16_f32 v0, v48, v49
	v_cvt_pk_bf16_f32 v1, v50, v51
	v_pk_fma_f32 v[34:35], v[142:143], v[34:35], v[26:27]
	v_pk_fma_f32 v[32:33], v[144:145], v[32:33], v[24:25]
	global_store_dwordx2 v[154:155], v[0:1], off offset:1536
	v_cvt_pk_bf16_f32 v0, v32, v33
	v_cvt_pk_bf16_f32 v1, v34, v35
	v_pk_add_f32 v[86:87], v[50:51], v[34:35]
	v_pk_add_f32 v[88:89], v[48:49], v[32:33]
	global_store_dwordx2 v[160:161], v[0:1], off offset:1536
	v_cvt_pk_bf16_f32 v0, v88, v89
	v_cvt_pk_bf16_f32 v1, v86, v87
	v_sub_f32_e32 v218, v50, v34
	v_sub_f32_e32 v219, v51, v35
	v_sub_f32_e32 v220, v48, v32
	v_sub_f32_e32 v221, v49, v33
	global_store_dwordx2 v[152:153], v[0:1], off offset:1536
	v_cvt_pk_bf16_f32 v0, v220, v221
	v_cvt_pk_bf16_f32 v1, v218, v219
	global_store_dwordx2 v[150:151], v[0:1], off offset:1536
	global_load_dwordx4 v[68:71], v[148:149], off nt
	global_load_dwordx4 v[60:63], v[158:159], off nt
	global_load_dwordx4 v[72:75], v[148:149], off offset:1024 nt
	global_load_dwordx4 v[52:55], v[158:159], off offset:1024 nt
	global_load_dwordx4 v[64:67], v[148:149], off offset:3072 nt
	global_load_dwordx4 v[76:79], v[148:149], off offset:2048 nt
	global_load_dwordx4 v[48:51], v[158:159], off offset:3072 nt
	global_load_dwordx4 v[56:59], v[158:159], off offset:2048 nt
	global_load_dwordx4 v[32:35], v[146:147], off nt
	global_load_dwordx4 v[4:7], v[156:157], off nt
	global_load_dwordx4 v[40:43], v[146:147], off offset:1024 nt
	global_load_dwordx4 v[8:11], v[156:157], off offset:1024 nt
	global_load_dwordx4 v[36:39], v[146:147], off offset:3072 nt
	global_load_dwordx4 v[44:47], v[146:147], off offset:2048 nt
	global_load_dwordx4 v[0:3], v[156:157], off offset:3072 nt
	global_load_dwordx4 v[12:15], v[156:157], off offset:2048 nt
	s_waitcnt vmcnt(15)
	v_pk_mul_f32 v[80:81], v[70:71], v[70:71]
	v_pk_mul_f32 v[82:83], v[68:69], v[68:69]
	s_waitcnt vmcnt(14)
; __device__ __forceinline__ void pass_h_fold(const float* src, const float* g, const float* mod, bf16_t* H, bf16_t* HE, bf16_t* HO) {
;     ...
;             for (int q = 0; q < 2; ++q) { const int s = sb + half * 2 + q, pr = (s == 0) ? SEQ / 2 : SEQ - s;
;                 float t0 = 0.f, t1 = 0.f;
; #pragma unroll
;                 for (int j = 0; j < 4; ++j) { const f32x4 a = v[q][0][j], c = v[q][1][j]; t0 += (a[0] * a[0] + a[1] * a[1]) + (a[2] * a[2] + a[3] * a[3]); t1 += (c[0] * c[0] + c[1] * c[1]) + (c[2] * c[2] + c[3] * c[3]); }
;                 t0 = wave_sum(t0); t1 = wave_sum(t1);
	v_pk_mul_f32 v[84:85], v[62:63], v[62:63]
	v_pk_mul_f32 v[86:87], v[60:61], v[60:61]
	s_waitcnt vmcnt(13)
	v_pk_mul_f32 v[88:89], v[74:75], v[74:75]
	v_pk_mul_f32 v[90:91], v[72:73], v[72:73]
	s_waitcnt vmcnt(12)
	v_pk_mul_f32 v[92:93], v[54:55], v[54:55]
	v_pk_mul_f32 v[94:95], v[52:53], v[52:53]
	s_waitcnt vmcnt(10)
	v_mul_f32_e32 v146, v77, v77
	v_mul_f32_e32 v148, v79, v79
	s_waitcnt vmcnt(8)
	v_mul_f32_e32 v150, v57, v57
	v_mul_f32_e32 v152, v59, v59
	s_waitcnt vmcnt(7)
	v_pk_mul_f32 v[154:155], v[34:35], v[34:35]
	v_pk_mul_f32 v[156:157], v[32:33], v[32:33]
	s_waitcnt vmcnt(6)
	v_pk_mul_f32 v[158:159], v[6:7], v[6:7]
	v_pk_mul_f32 v[160:161], v[4:5], v[4:5]
	s_waitcnt vmcnt(5)
	v_pk_mul_f32 v[162:163], v[42:43], v[42:43]
	v_pk_mul_f32 v[164:165], v[40:41], v[40:41]
	v_pk_mov_b32 v[192:193], v[82:83], v[80:81] op_sel:[1,0]
	v_mov_b32_e32 v83, v81
	v_pk_mov_b32 v[80:81], v[86:87], v[84:85] op_sel:[1,0]
	v_mov_b32_e32 v87, v85
	v_pk_mov_b32 v[84:85], v[90:91], v[88:89] op_sel:[1,0]
	v_mov_b32_e32 v91, v89
	s_waitcnt vmcnt(4)
	v_pk_mul_f32 v[166:167], v[10:11], v[10:11]
	v_pk_mul_f32 v[168:169], v[8:9], v[8:9]
	v_pk_mov_b32 v[88:89], v[94:95], v[92:93] op_sel:[1,0]
	v_mov_b32_e32 v95, v93
	v_pk_fma_f32 v[92:93], v[76:77], v[76:77], v[146:147] op_sel_hi:[1,1,0]
	v_pk_fma_f32 v[146:147], v[78:79], v[78:79], v[148:149] op_sel_hi:[1,1,0]
	v_pk_fma_f32 v[148:149], v[56:57], v[56:57], v[150:151] op_sel_hi:[1,1,0]
	v_pk_fma_f32 v[150:151], v[58:59], v[58:59], v[152:153] op_sel_hi:[1,1,0]
	v_pk_mov_b32 v[152:153], v[156:157], v[154:155] op_sel:[1,0]
	v_mov_b32_e32 v157, v155
	v_pk_mov_b32 v[154:155], v[160:161], v[158:159] op_sel:[1,0]
	v_mov_b32_e32 v161, v159
	v_pk_mov_b32 v[158:159], v[164:165], v[162:163] op_sel:[1,0]
	v_mov_b32_e32 v165, v163
	v_pk_add_f32 v[82:83], v[192:193], v[82:83]
	v_pk_add_f32 v[84:85], v[84:85], v[90:91]
	v_mul_f32_e32 v191, v64, v64
	v_mul_f32_e32 v194, v65, v65
	v_mul_f32_e32 v195, v66, v66
	v_mul_f32_e32 v196, v67, v67
	v_mul_f32_e32 v199, v50, v50
	v_mul_f32_e32 v200, v51, v51
	s_waitcnt vmcnt(2)
	v_mul_f32_e32 v184, v45, v45
	v_mul_f32_e32 v186, v47, v47
	v_pk_mov_b32 v[162:163], v[168:169], v[166:167] op_sel:[1,0]
	v_mov_b32_e32 v169, v167
	v_pk_add_f32 v[80:81], v[80:81], v[86:87]
	v_pk_add_f32 v[86:87], v[88:89], v[94:95]
	v_pk_add_f32 v[88:89], v[152:153], v[156:157]
	v_pk_add_f32 v[94:95], v[158:159], v[164:165]
	v_pk_add_f32 v[82:83], v[82:83], v[82:83] op_sel:[0,1] op_sel_hi:[1,0]
	v_pk_add_f32 v[84:85], v[84:85], v[84:85] op_sel:[0,1] op_sel_hi:[1,0]
	v_mul_f32_e32 v197, v48, v48
	v_mul_f32_e32 v198, v49, v49
	v_mul_f32_e32 v201, v36, v36
	v_mul_f32_e32 v202, v37, v37
	v_mul_f32_e32 v203, v38, v38
	v_mul_f32_e32 v204, v39, v39
	s_waitcnt vmcnt(0)
	v_mul_f32_e32 v188, v13, v13
	v_mul_f32_e32 v190, v15, v15
	v_pk_fma_f32 v[166:167], v[44:45], v[44:45], v[184:185] op_sel_hi:[1,1,0]
	v_pk_fma_f32 v[184:185], v[46:47], v[46:47], v[186:187] op_sel_hi:[1,1,0]
	v_mov_b32_e32 v93, v195
	v_mov_b32_e32 v147, v196
	v_mov_b32_e32 v149, v199
	v_mov_b32_e32 v151, v200
	v_pk_add_f32 v[90:91], v[154:155], v[160:161]
	v_pk_add_f32 v[152:153], v[162:163], v[168:169]
	v_pk_add_f32 v[80:81], v[80:81], v[80:81] op_sel:[0,1] op_sel_hi:[1,0]
	v_pk_add_f32 v[86:87], v[86:87], v[86:87] op_sel:[0,1] op_sel_hi:[1,0]
	v_pk_add_f32 v[88:89], v[88:89], v[88:89] op_sel:[0,1] op_sel_hi:[1,0]
	v_pk_add_f32 v[94:95], v[94:95], v[94:95] op_sel:[0,1] op_sel_hi:[1,0]
	v_mov_b32_e32 v83, v191
	v_mov_b32_e32 v85, v194
	v_mul_f32_e32 v205, v0, v0
	v_mul_f32_e32 v206, v1, v1
	v_mul_f32_e32 v207, v2, v2
	v_mul_f32_e32 v208, v3, v3
	v_pk_fma_f32 v[186:187], v[12:13], v[12:13], v[188:189] op_sel_hi:[1,1,0]
	v_pk_fma_f32 v[188:189], v[14:15], v[14:15], v[190:191] op_sel_hi:[1,1,0]
	v_mov_b32_e32 v167, v203
	v_mov_b32_e32 v185, v204
	v_pk_add_f32 v[92:93], v[92:93], v[146:147]
	v_pk_add_f32 v[146:147], v[148:149], v[150:151]
	v_pk_add_f32 v[90:91], v[90:91], v[90:91] op_sel:[0,1] op_sel_hi:[1,0]
	v_pk_add_f32 v[150:151], v[152:153], v[152:153] op_sel:[0,1] op_sel_hi:[1,0]
	v_mov_b32_e32 v81, v197
	v_mov_b32_e32 v87, v198
	v_mov_b32_e32 v89, v201
	v_mov_b32_e32 v95, v202
	v_pk_add_f32 v[82:83], v[82:83], v[84:85]
	v_mov_b32_e32 v187, v207
	v_mov_b32_e32 v189, v208
	v_pk_add_f32 v[148:149], v[166:167], v[184:185]
	v_mov_b32_e32 v91, v205
	v_mov_b32_e32 v151, v206
	v_pk_add_f32 v[80:81], v[80:81], v[86:87]
	v_pk_add_f32 v[84:85], v[88:89], v[94:95]
	v_pk_add_f32 v[82:83], v[82:83], v[92:93]
	v_pk_add_f32 v[152:153], v[186:187], v[188:189]
	v_pk_add_f32 v[86:87], v[90:91], v[150:151]
	v_pk_add_f32 v[80:81], v[80:81], v[146:147]
	v_pk_add_f32 v[84:85], v[84:85], v[148:149]
	v_add_f32_e32 v82, v82, v83
	v_pk_add_f32 v[86:87], v[86:87], v[152:153]
	v_add_f32_e32 v80, v80, v81
	v_add_f32_e32 v81, v84, v85
	ds_bpermute_b32 v84, v174, v82
	v_add_f32_e32 v83, v86, v87
	ds_bpermute_b32 v85, v174, v80
	ds_bpermute_b32 v86, v174, v81
	ds_bpermute_b32 v87, v174, v83
	s_waitcnt lgkmcnt(3)
	v_add_f32_e32 v82, v82, v84
	ds_bpermute_b32 v84, v175, v82
	s_waitcnt lgkmcnt(3)
	v_add_f32_e32 v80, v80, v85
	s_waitcnt lgkmcnt(2)
	v_add_f32_e32 v81, v81, v86
	ds_bpermute_b32 v85, v175, v80
	ds_bpermute_b32 v86, v175, v81
	s_waitcnt lgkmcnt(3)
	v_add_f32_e32 v83, v83, v87
	ds_bpermute_b32 v87, v175, v83
	s_waitcnt lgkmcnt(3)
	v_add_f32_e32 v82, v82, v84
	s_waitcnt lgkmcnt(2)
	v_add_f32_e32 v80, v80, v85
	s_waitcnt lgkmcnt(1)
	v_add_f32_e32 v81, v81, v86
	ds_bpermute_b32 v84, v176, v82
	ds_bpermute_b32 v85, v176, v80
	ds_bpermute_b32 v86, v176, v81
	s_waitcnt lgkmcnt(3)
	v_add_f32_e32 v83, v83, v87
	ds_bpermute_b32 v87, v176, v83
	s_waitcnt lgkmcnt(3)
; __device__ __forceinline__ void pass_h_fold(const float* src, const float* g, const float* mod, bf16_t* H, bf16_t* HE, bf16_t* HO) {
;     ...
;                 t0 = wave_sum(t0); t1 = wave_sum(t1);
;                 const float r0 = 1.0f / sqrtf(t0 * (1.0f / DM) + EPS), r1 = 1.0f / sqrtf(t1 * (1.0f / DM) + EPS);
;                 u32x2* o0 = (u32x2*)(H + (size_t)(b * SEQ + s) * DM) + lane; u32x2* o1 = (u32x2*)(H + (size_t)(b * SEQ + pr) * DM) + lane;
;                 u32x2* oe = (u32x2*)(HE + (size_t)(b * 1024 + s) * DM) + lane; u32x2* oo = (u32x2*)(HO + (size_t)(b * 1024 + s) * DM) + lane;
; #pragma unroll
;                 for (int j = 0; j < 4; ++j) { const f32x4 h0 = (v[q][0][j] * r0) * mul[j] + sh[j], h1 = (v[q][1][j] * r1) * mul[j] + sh[j];
	v_add_f32_e32 v82, v82, v84
	s_waitcnt lgkmcnt(2)
	v_add_f32_e32 v80, v80, v85
	s_waitcnt lgkmcnt(1)
	v_add_f32_e32 v81, v81, v86
	ds_bpermute_b32 v84, v177, v82
	ds_bpermute_b32 v85, v177, v80
	ds_bpermute_b32 v86, v177, v81
	s_waitcnt lgkmcnt(3)
	v_add_f32_e32 v83, v83, v87
	ds_bpermute_b32 v87, v177, v83
	s_waitcnt lgkmcnt(3)
	v_add_f32_e32 v82, v82, v84
	s_waitcnt lgkmcnt(2)
	v_add_f32_e32 v80, v80, v85
	s_waitcnt lgkmcnt(1)
	v_add_f32_e32 v81, v81, v86
	ds_bpermute_b32 v84, v178, v82
	ds_bpermute_b32 v85, v178, v80
	ds_bpermute_b32 v86, v178, v81
	s_waitcnt lgkmcnt(3)
	v_add_f32_e32 v83, v83, v87
	ds_bpermute_b32 v87, v178, v83
	s_waitcnt lgkmcnt(3)
	v_add_f32_e32 v82, v82, v84
	s_waitcnt lgkmcnt(2)
	v_add_f32_e32 v80, v80, v85
	s_waitcnt lgkmcnt(1)
	v_add_f32_e32 v81, v81, v86
	ds_bpermute_b32 v84, v179, v82
	ds_bpermute_b32 v85, v179, v80
	ds_bpermute_b32 v86, v179, v81
	s_waitcnt lgkmcnt(3)
	v_add_f32_e32 v83, v83, v87
	ds_bpermute_b32 v87, v179, v83
	s_waitcnt lgkmcnt(3)
	v_add_f32_e32 v82, v82, v84
	s_waitcnt lgkmcnt(2)
	v_add_f32_e32 v80, v80, v85
	s_waitcnt lgkmcnt(1)
	v_add_f32_e32 v81, v81, v86
	v_fmamk_f32 v82, v82, 0x3a800000, v182
	v_fmamk_f32 v80, v80, 0x3a800000, v182
	v_fmamk_f32 v81, v81, 0x3a800000, v182
	v_mul_f32_e32 v84, 0x4f800000, v82
	v_cmp_gt_f32_e64 s[8:9], s40, v82
	v_mul_f32_e32 v85, 0x4f800000, v80
	v_cmp_gt_f32_e32 vcc, s40, v80
	v_mul_f32_e32 v86, 0x4f800000, v81
	v_cmp_gt_f32_e64 s[4:5], s40, v81
	v_cndmask_b32_e64 v82, v82, v84, s[8:9]
	s_waitcnt lgkmcnt(0)
	v_add_f32_e32 v83, v83, v87
	v_cndmask_b32_e32 v80, v80, v85, vcc
	v_cndmask_b32_e64 v81, v81, v86, s[4:5]
	v_sqrt_f32_e32 v84, v82
	v_fmamk_f32 v83, v83, 0x3a800000, v182
	v_sqrt_f32_e32 v85, v80
	v_sqrt_f32_e32 v86, v81
	v_mul_f32_e32 v87, 0x4f800000, v83
	v_cmp_gt_f32_e64 s[6:7], s40, v83
	v_add_u32_e32 v88, -1, v84
	v_add_u32_e32 v89, 1, v84
	v_cndmask_b32_e64 v83, v83, v87, s[6:7]
	v_sqrt_f32_e32 v87, v83
	v_add_u32_e32 v90, -1, v85
	v_add_u32_e32 v92, -1, v86
	v_fma_f32 v146, -v88, v84, v82
	v_add_u32_e32 v91, 1, v85
	v_add_u32_e32 v93, 1, v86
	v_fma_f32 v147, -v89, v84, v82
	v_fma_f32 v148, -v90, v85, v80
	v_fma_f32 v150, -v92, v86, v81
	v_cmp_ge_f32_e64 s[12:13], 0, v146
	v_fma_f32 v149, -v91, v85, v80
	v_fma_f32 v151, -v93, v86, v81
	v_cndmask_b32_e64 v84, v84, v88, s[12:13]
	v_cmp_ge_f32_e64 s[12:13], 0, v148
	v_cmp_ge_f32_e64 s[14:15], 0, v150
	v_cmp_lt_f32_e64 s[18:19], 0, v147
	v_add_u32_e32 v94, -1, v87
	v_cndmask_b32_e64 v85, v85, v90, s[12:13]
	v_cmp_lt_f32_e64 s[12:13], 0, v149
	v_cndmask_b32_e64 v86, v86, v92, s[14:15]
	v_cmp_lt_f32_e64 s[14:15], 0, v151
	v_cndmask_b32_e64 v84, v84, v89, s[18:19]
	v_add_u32_e32 v95, 1, v87
	v_fma_f32 v152, -v94, v87, v83
	v_cndmask_b32_e64 v85, v85, v91, s[12:13]
	v_cndmask_b32_e64 v86, v86, v93, s[14:15]
	v_mul_f32_e32 v88, 0x37800000, v84
	v_fma_f32 v153, -v95, v87, v83
	v_cmp_ge_f32_e64 s[16:17], 0, v152
	v_mul_f32_e32 v89, 0x37800000, v85
	v_mul_f32_e32 v90, 0x37800000, v86
	v_cndmask_b32_e64 v84, v84, v88, s[8:9]
	v_cmp_class_f32_e64 s[8:9], v82, v183
	v_cndmask_b32_e64 v87, v87, v94, s[16:17]
	v_cmp_lt_f32_e64 s[16:17], 0, v153
	v_cndmask_b32_e32 v85, v85, v89, vcc
	v_cmp_class_f32_e32 vcc, v80, v183
	v_cndmask_b32_e64 v86, v86, v90, s[4:5]
	v_cmp_class_f32_e64 s[4:5], v81, v183
	v_cndmask_b32_e64 v82, v84, v82, s[8:9]
	v_cndmask_b32_e64 v87, v87, v95, s[16:17]
	v_cndmask_b32_e32 v84, v85, v80, vcc
	v_cndmask_b32_e64 v81, v86, v81, s[4:5]
	v_div_scale_f32 v80, s[4:5], v82, v82, 1.0
	v_mul_f32_e32 v91, 0x37800000, v87
	v_div_scale_f32 v86, s[4:5], v84, v84, 1.0
	v_rcp_f32_e32 v92, v80
	v_cndmask_b32_e64 v87, v87, v91, s[6:7]
	v_cmp_class_f32_e64 s[6:7], v83, v183
	v_rcp_f32_e32 v93, v86
	v_fma_f32 v146, -v80, v92, 1.0
	v_cndmask_b32_e64 v85, v87, v83, s[6:7]
	v_div_scale_f32 v88, s[6:7], v81, v81, 1.0
	v_div_scale_f32 v90, s[8:9], v85, v85, 1.0
	v_rcp_f32_e32 v94, v88
	v_rcp_f32_e32 v95, v90
	v_div_scale_f32 v83, vcc, 1.0, v82, 1.0
	v_fma_f32 v147, -v86, v93, 1.0
	v_fmac_f32_e32 v92, v146, v92
	v_div_scale_f32 v87, s[4:5], 1.0, v84, 1.0
	v_fmac_f32_e32 v93, v147, v93
	v_mul_f32_e32 v146, v83, v92
	v_fma_f32 v148, -v88, v94, 1.0
	v_mul_f32_e32 v147, v87, v93
	v_fma_f32 v150, -v80, v146, v83
	v_div_scale_f32 v89, s[6:7], 1.0, v81, 1.0
	v_fma_f32 v149, -v90, v95, 1.0
	v_fmac_f32_e32 v94, v148, v94
	v_fma_f32 v151, -v86, v147, v87
	v_fmac_f32_e32 v146, v150, v92
	v_div_scale_f32 v91, s[8:9], 1.0, v85, 1.0
	v_fmac_f32_e32 v95, v149, v95
	v_mul_f32_e32 v148, v89, v94
	v_fmac_f32_e32 v147, v151, v93
	v_fma_f32 v80, -v80, v146, v83
	v_mul_f32_e32 v149, v91, v95
	v_fma_f32 v152, -v88, v148, v89
	v_fma_f32 v83, -v86, v147, v87
	v_div_fmas_f32 v80, v80, v92, v146
	s_mov_b64 vcc, s[4:5]
	v_fma_f32 v153, -v90, v149, v91
	v_fmac_f32_e32 v148, v152, v94
	v_div_fixup_f32 v80, v80, v82, 1.0
	v_div_fmas_f32 v82, v83, v93, v147
	v_fmac_f32_e32 v149, v153, v95
	v_fma_f32 v86, -v88, v148, v89
	v_div_fixup_f32 v82, v82, v84, 1.0
	s_mov_b64 vcc, s[6:7]
	v_fma_f32 v87, -v90, v149, v91
	v_pk_mul_f32 v[68:69], v[68:69], v[80:81] op_sel_hi:[1,0]
	v_pk_mul_f32 v[70:71], v[70:71], v[80:81] op_sel_hi:[1,0]
	v_pk_mul_f32 v[72:73], v[72:73], v[80:81] op_sel_hi:[1,0]
	v_pk_mul_f32 v[74:75], v[74:75], v[80:81] op_sel_hi:[1,0]
	v_pk_mul_f32 v[76:77], v[76:77], v[80:81] op_sel_hi:[1,0]
	v_pk_mul_f32 v[78:79], v[78:79], v[80:81] op_sel_hi:[1,0]
	v_pk_mul_f32 v[64:65], v[64:65], v[80:81] op_sel_hi:[1,0]
	v_pk_mul_f32 v[66:67], v[66:67], v[80:81] op_sel_hi:[1,0]
	v_div_fmas_f32 v80, v86, v94, v148
	v_pk_mul_f32 v[62:63], v[62:63], v[82:83] op_sel_hi:[1,0]
	s_mov_b64 vcc, s[8:9]
	v_pk_fma_f32 v[70:71], v[130:131], v[70:71], v[30:31]
; __device__ __forceinline__ unsigned cvt_pk_bf16(float lo, float hi) { unsigned r; asm volatile("v_cvt_pk_bf16_f32 %0, %1, %2" : "=v"(r) : "v"(lo), "v"(hi)); return r; }
; __device__ __forceinline__ void pass_h_fold(const float* src, const float* g, const float* mod, bf16_t* H, bf16_t* HE, bf16_t* HO) {
;     ...
;                 u32x2* o0 = (u32x2*)(H + (size_t)(b * SEQ + s) * DM) + lane; u32x2* o1 = (u32x2*)(H + (size_t)(b * SEQ + pr) * DM) + lane;
;                 u32x2* oe = (u32x2*)(HE + (size_t)(b * 1024 + s) * DM) + lane; u32x2* oo = (u32x2*)(HO + (size_t)(b * 1024 + s) * DM) + lane;
; #pragma unroll
;                 for (int j = 0; j < 4; ++j) { const f32x4 h0 = (v[q][0][j] * r0) * mul[j] + sh[j], h1 = (v[q][1][j] * r1) * mul[j] + sh[j];
;                     u32x2 w; w.x = cvt_pk_bf16(h0[0], h0[1]); w.y = cvt_pk_bf16(h0[2], h0[3]); o0[64 * j] = w;
;                     w.x = cvt_pk_bf16(h1[0], h1[1]); w.y = cvt_pk_bf16(h1[2], h1[3]); o1[64 * j] = w;
;                     const f32x4 e = (s == 0) ? h0 : h0 + h1, o = (s == 0) ? (f32x4){0.f, 0.f, 0.f, 0.f} : h0 - h1;
;                     w.x = cvt_pk_bf16(e[0], e[1]); w.y = cvt_pk_bf16(e[2], e[3]); oe[64 * j] = w;
;                     w.x = cvt_pk_bf16(o[0], o[1]); w.y = cvt_pk_bf16(o[2], o[3]); oo[64 * j] = w; } }
	v_div_fixup_f32 v80, v80, v81, 1.0
	v_div_fmas_f32 v81, v87, v95, v149
	v_pk_fma_f32 v[62:63], v[130:131], v[62:63], v[30:31]
	v_pk_mul_f32 v[60:61], v[60:61], v[82:83] op_sel_hi:[1,0]
	v_div_fixup_f32 v84, v81, v85, 1.0
	v_sub_f32_e32 v85, v70, v62
	v_pk_fma_f32 v[68:69], v[132:133], v[68:69], v[28:29]
	v_pk_mul_f32 v[52:53], v[52:53], v[82:83] op_sel_hi:[1,0]
	v_pk_mul_f32 v[54:55], v[54:55], v[82:83] op_sel_hi:[1,0]
	v_pk_mul_f32 v[56:57], v[56:57], v[82:83] op_sel_hi:[1,0]
	v_pk_mul_f32 v[58:59], v[58:59], v[82:83] op_sel_hi:[1,0]
	v_pk_mul_f32 v[48:49], v[48:49], v[82:83] op_sel_hi:[1,0]
	v_pk_mul_f32 v[50:51], v[50:51], v[82:83] op_sel_hi:[1,0]
	v_pk_fma_f32 v[60:61], v[132:133], v[60:61], v[28:29]
	v_cvt_pk_bf16_f32 v82, v68, v69
	v_cvt_pk_bf16_f32 v83, v70, v71
	v_pk_mul_f32 v[32:33], v[32:33], v[80:81] op_sel_hi:[1,0]
	v_pk_mul_f32 v[34:35], v[34:35], v[80:81] op_sel_hi:[1,0]
	v_pk_mul_f32 v[40:41], v[40:41], v[80:81] op_sel_hi:[1,0]
	v_pk_mul_f32 v[42:43], v[42:43], v[80:81] op_sel_hi:[1,0]
	v_pk_mul_f32 v[44:45], v[44:45], v[80:81] op_sel_hi:[1,0]
	v_pk_mul_f32 v[46:47], v[46:47], v[80:81] op_sel_hi:[1,0]
	v_pk_mul_f32 v[36:37], v[36:37], v[80:81] op_sel_hi:[1,0]
	v_pk_mul_f32 v[38:39], v[38:39], v[80:81] op_sel_hi:[1,0]
	global_store_dwordx2 v[126:127], v[82:83], off
	v_cvt_pk_bf16_f32 v80, v60, v61
	v_cvt_pk_bf16_f32 v81, v62, v63
	v_pk_mul_f32 v[12:13], v[12:13], v[84:85] op_sel_hi:[1,0]
	v_pk_fma_f32 v[76:77], v[140:141], v[76:77], v[16:17]
	v_pk_fma_f32 v[56:57], v[140:141], v[56:57], v[16:17]
	v_pk_add_f32 v[82:83], v[70:71], v[62:63]
	v_pk_add_f32 v[86:87], v[68:69], v[60:61]
	v_sub_f32_e32 v92, v71, v63
	v_sub_f32_e32 v93, v68, v60
	v_sub_f32_e32 v94, v69, v61
	v_pk_fma_f32 v[44:45], v[140:141], v[44:45], v[16:17]
	global_store_dwordx2 v[128:129], v[80:81], off
	v_cvt_pk_bf16_f32 v80, v86, v87
	v_cvt_pk_bf16_f32 v81, v82, v83
	v_pk_fma_f32 v[12:13], v[140:141], v[12:13], v[16:17]
	global_store_dwordx2 v[124:125], v[80:81], off
	v_cvt_pk_bf16_f32 v16, v93, v94
	v_cvt_pk_bf16_f32 v17, v85, v92
	v_pk_fma_f32 v[74:75], v[134:135], v[74:75], v[22:23]
	v_pk_fma_f32 v[72:73], v[136:137], v[72:73], v[20:21]
	global_store_dwordx2 v[122:123], v[16:17], off
	v_cvt_pk_bf16_f32 v16, v72, v73
	v_cvt_pk_bf16_f32 v17, v74, v75
	v_pk_fma_f32 v[54:55], v[134:135], v[54:55], v[22:23]
	v_pk_fma_f32 v[52:53], v[136:137], v[52:53], v[20:21]
	global_store_dwordx2 v[126:127], v[16:17], off offset:512
	v_cvt_pk_bf16_f32 v16, v52, v53
	v_cvt_pk_bf16_f32 v17, v54, v55
	v_pk_add_f32 v[60:61], v[74:75], v[54:55]
	v_pk_add_f32 v[62:63], v[72:73], v[52:53]
	global_store_dwordx2 v[128:129], v[16:17], off offset:512
	v_cvt_pk_bf16_f32 v16, v62, v63
	v_cvt_pk_bf16_f32 v17, v60, v61
	v_sub_f32_e32 v95, v74, v54
	v_sub_f32_e32 v146, v75, v55
	v_sub_f32_e32 v147, v72, v52
	v_sub_f32_e32 v148, v73, v53
	global_store_dwordx2 v[124:125], v[16:17], off offset:512
	v_cvt_pk_bf16_f32 v16, v147, v148
	v_cvt_pk_bf16_f32 v17, v95, v146
	v_pk_fma_f32 v[78:79], v[138:139], v[78:79], v[18:19]
	global_store_dwordx2 v[122:123], v[16:17], off offset:512
	v_cvt_pk_bf16_f32 v16, v76, v77
	v_cvt_pk_bf16_f32 v17, v78, v79
	v_pk_fma_f32 v[58:59], v[138:139], v[58:59], v[18:19]
	global_store_dwordx2 v[126:127], v[16:17], off offset:1024
	v_cvt_pk_bf16_f32 v16, v56, v57
	v_cvt_pk_bf16_f32 v17, v58, v59
	v_pk_add_f32 v[68:69], v[78:79], v[58:59]
	v_pk_add_f32 v[70:71], v[76:77], v[56:57]
	global_store_dwordx2 v[128:129], v[16:17], off offset:1024
	v_cvt_pk_bf16_f32 v16, v70, v71
	v_cvt_pk_bf16_f32 v17, v68, v69
	v_sub_f32_e32 v149, v78, v58
	v_sub_f32_e32 v150, v79, v59
	v_sub_f32_e32 v151, v76, v56
	v_sub_f32_e32 v152, v77, v57
	global_store_dwordx2 v[124:125], v[16:17], off offset:1024
	v_cvt_pk_bf16_f32 v16, v151, v152
	v_cvt_pk_bf16_f32 v17, v149, v150
	v_pk_fma_f32 v[66:67], v[142:143], v[66:67], v[26:27]
	v_pk_fma_f32 v[64:65], v[144:145], v[64:65], v[24:25]
	global_store_dwordx2 v[122:123], v[16:17], off offset:1024
	v_cvt_pk_bf16_f32 v16, v64, v65
	v_cvt_pk_bf16_f32 v17, v66, v67
	v_pk_fma_f32 v[50:51], v[142:143], v[50:51], v[26:27]
	v_pk_fma_f32 v[48:49], v[144:145], v[48:49], v[24:25]
	global_store_dwordx2 v[126:127], v[16:17], off offset:1536
	v_cvt_pk_bf16_f32 v16, v48, v49
	v_cvt_pk_bf16_f32 v17, v50, v51
	v_pk_add_f32 v[88:89], v[66:67], v[50:51]
	v_pk_add_f32 v[90:91], v[64:65], v[48:49]
; __device__ __forceinline__ unsigned cvt_pk_bf16(float lo, float hi) { unsigned r; asm volatile("v_cvt_pk_bf16_f32 %0, %1, %2" : "=v"(r) : "v"(lo), "v"(hi)); return r; }
; __device__ __forceinline__ void pass_h_fold(const float* src, const float* g, const float* mod, bf16_t* H, bf16_t* HE, bf16_t* HO) {
;     ...
;                 for (int j = 0; j < 4; ++j) { const f32x4 h0 = (v[q][0][j] * r0) * mul[j] + sh[j], h1 = (v[q][1][j] * r1) * mul[j] + sh[j];
;                     u32x2 w; w.x = cvt_pk_bf16(h0[0], h0[1]); w.y = cvt_pk_bf16(h0[2], h0[3]); o0[64 * j] = w;
;                     w.x = cvt_pk_bf16(h1[0], h1[1]); w.y = cvt_pk_bf16(h1[2], h1[3]); o1[64 * j] = w;
;                     const f32x4 e = (s == 0) ? h0 : h0 + h1, o = (s == 0) ? (f32x4){0.f, 0.f, 0.f, 0.f} : h0 - h1;
;                     w.x = cvt_pk_bf16(e[0], e[1]); w.y = cvt_pk_bf16(e[2], e[3]); oe[64 * j] = w;
;                     w.x = cvt_pk_bf16(o[0], o[1]); w.y = cvt_pk_bf16(o[2], o[3]); oo[64 * j] = w; } }
	v_pk_mul_f32 v[4:5], v[4:5], v[84:85] op_sel_hi:[1,0]
	global_store_dwordx2 v[128:129], v[16:17], off offset:1536
	v_cvt_pk_bf16_f32 v16, v90, v91
	v_cvt_pk_bf16_f32 v17, v88, v89
	v_sub_f32_e32 v153, v66, v50
	v_sub_f32_e32 v154, v67, v51
	v_sub_f32_e32 v155, v64, v48
	v_sub_f32_e32 v156, v65, v49
	v_pk_fma_f32 v[32:33], v[132:133], v[32:33], v[28:29]
	v_pk_mul_f32 v[6:7], v[6:7], v[84:85] op_sel_hi:[1,0]
	v_pk_mul_f32 v[8:9], v[8:9], v[84:85] op_sel_hi:[1,0]
	v_pk_fma_f32 v[4:5], v[132:133], v[4:5], v[28:29]
	global_store_dwordx2 v[124:125], v[16:17], off offset:1536
	v_cvt_pk_bf16_f32 v16, v155, v156
	v_cvt_pk_bf16_f32 v17, v153, v154
	v_pk_fma_f32 v[34:35], v[130:131], v[34:35], v[30:31]
	v_pk_fma_f32 v[40:41], v[136:137], v[40:41], v[20:21]
	v_pk_mul_f32 v[10:11], v[10:11], v[84:85] op_sel_hi:[1,0]
	v_pk_mul_f32 v[14:15], v[14:15], v[84:85] op_sel_hi:[1,0]
	v_pk_mul_f32 v[0:1], v[0:1], v[84:85] op_sel_hi:[1,0]
	v_pk_mul_f32 v[2:3], v[2:3], v[84:85] op_sel_hi:[1,0]
	v_pk_fma_f32 v[6:7], v[130:131], v[6:7], v[30:31]
	v_pk_fma_f32 v[8:9], v[136:137], v[8:9], v[20:21]
	v_pk_add_f32 v[20:21], v[32:33], v[4:5]
	v_sub_f32_e32 v84, v32, v4
	v_sub_f32_e32 v85, v33, v5
	global_store_dwordx2 v[122:123], v[16:17], off offset:1536
	v_cvt_pk_bf16_f32 v16, v32, v33
	v_cvt_pk_bf16_f32 v17, v34, v35
	global_store_dwordx2 v[118:119], v[16:17], off
	v_cvt_pk_bf16_f32 v4, v4, v5
	v_cvt_pk_bf16_f32 v5, v6, v7
	v_pk_fma_f32 v[46:47], v[138:139], v[46:47], v[18:19]
	v_pk_fma_f32 v[14:15], v[138:139], v[14:15], v[18:19]
	v_pk_add_f32 v[18:19], v[34:35], v[6:7]
	global_store_dwordx2 v[120:121], v[4:5], off
	v_cvt_pk_bf16_f32 v4, v20, v21
	v_cvt_pk_bf16_f32 v5, v18, v19
	v_sub_f32_e32 v82, v34, v6
	v_sub_f32_e32 v83, v35, v7
	global_store_dwordx2 v[116:117], v[4:5], off
	v_cvt_pk_bf16_f32 v4, v84, v85
	v_cvt_pk_bf16_f32 v5, v82, v83
	v_pk_fma_f32 v[42:43], v[134:135], v[42:43], v[22:23]
	global_store_dwordx2 v[114:115], v[4:5], off
	v_cvt_pk_bf16_f32 v4, v40, v41
	v_cvt_pk_bf16_f32 v5, v42, v43
	v_pk_fma_f32 v[10:11], v[134:135], v[10:11], v[22:23]
	global_store_dwordx2 v[118:119], v[4:5], off offset:512
	v_cvt_pk_bf16_f32 v4, v8, v9
	v_cvt_pk_bf16_f32 v5, v10, v11
	v_pk_fma_f32 v[36:37], v[144:145], v[36:37], v[24:25]
	v_pk_fma_f32 v[0:1], v[144:145], v[0:1], v[24:25]
	v_pk_add_f32 v[22:23], v[42:43], v[10:11]
	v_pk_add_f32 v[24:25], v[40:41], v[8:9]
	global_store_dwordx2 v[120:121], v[4:5], off offset:512
	v_cvt_pk_bf16_f32 v4, v24, v25
	v_cvt_pk_bf16_f32 v5, v22, v23
	v_sub_f32_e32 v86, v42, v10
	v_sub_f32_e32 v87, v43, v11
	v_sub_f32_e32 v92, v40, v8
	v_sub_f32_e32 v93, v41, v9
	global_store_dwordx2 v[116:117], v[4:5], off offset:512
	v_cvt_pk_bf16_f32 v4, v92, v93
	v_cvt_pk_bf16_f32 v5, v86, v87
	global_store_dwordx2 v[114:115], v[4:5], off offset:512
	v_cvt_pk_bf16_f32 v4, v44, v45
	v_cvt_pk_bf16_f32 v5, v46, v47
	global_store_dwordx2 v[118:119], v[4:5], off offset:1024
	v_cvt_pk_bf16_f32 v4, v12, v13
	v_cvt_pk_bf16_f32 v5, v14, v15
	v_pk_fma_f32 v[38:39], v[142:143], v[38:39], v[26:27]
	v_pk_fma_f32 v[2:3], v[142:143], v[2:3], v[26:27]
	v_pk_add_f32 v[26:27], v[46:47], v[14:15]
	v_pk_add_f32 v[28:29], v[44:45], v[12:13]
	global_store_dwordx2 v[120:121], v[4:5], off offset:1024
	v_cvt_pk_bf16_f32 v4, v28, v29
	v_cvt_pk_bf16_f32 v5, v26, v27
	v_sub_f32_e32 v94, v46, v14
	v_sub_f32_e32 v130, v47, v15
	v_sub_f32_e32 v131, v44, v12
	v_sub_f32_e32 v132, v45, v13
	global_store_dwordx2 v[116:117], v[4:5], off offset:1024
	v_cvt_pk_bf16_f32 v4, v131, v132
	v_cvt_pk_bf16_f32 v5, v94, v130
	v_pk_add_f32 v[80:81], v[36:37], v[0:1]
	v_sub_f32_e32 v135, v36, v0
	v_sub_f32_e32 v136, v37, v1
	global_store_dwordx2 v[114:115], v[4:5], off offset:1024
	v_cvt_pk_bf16_f32 v4, v36, v37
	v_cvt_pk_bf16_f32 v5, v38, v39
	global_store_dwordx2 v[118:119], v[4:5], off offset:1536
	v_cvt_pk_bf16_f32 v0, v0, v1
	v_cvt_pk_bf16_f32 v1, v2, v3
	v_pk_add_f32 v[30:31], v[38:39], v[2:3]
	global_store_dwordx2 v[120:121], v[0:1], off offset:1536
	v_cvt_pk_bf16_f32 v0, v80, v81
	v_cvt_pk_bf16_f32 v1, v30, v31
	v_sub_f32_e32 v133, v38, v2
	v_sub_f32_e32 v134, v39, v3
	global_store_dwordx2 v[116:117], v[0:1], off offset:1536
	v_cvt_pk_bf16_f32 v0, v135, v136
	v_cvt_pk_bf16_f32 v1, v133, v134
	global_store_dwordx2 v[114:115], v[0:1], off offset:1536
	s_andn2_b64 exec, exec, s[22:23]
	s_cbranch_execnz .LBB0_99
